# v13 plus out-proj epilogue: first 8 residual loads of the second row-half prefetched as dwordx2 together with the first half's loads (removes a second exposed load latency and a store drain per unit)
# speedup vs baseline: 1.0045x; 1.0045x over previous
; #define LAS __attribute__((address_space(3)))
; #define NTLD(p) __builtin_nontemporal_load(p)
;     __device__ __forceinline__ void operator()(const f32x4 (&acc)[2][2][4][2], const pg8::Unit& u, int wr, int wc, int fr, int fq) const {
;     ...
;         const int pm = u.pm; const bool sample = pm >= (MP / 256);
;         const bf16* xb = xbf + (size_t)pm * 256 * DM;
;         float* ob = sample ? out + OUT_YS + (size_t)(pm - MP / 256) * 256 * DM : out + OUT_YP + (size_t)pm * 256 * DM;
;         LAS unsigned char* T = stg + (wr * 4 + wc) * 2048;
;         const int lane = fr + 16 * fq, rr = lane >> 3, p = lane & 7;
;         const int woff0 = fr * 128 + ((fq ^ (fr & 7)) << 4), woff1 = fr * 128 + (((4 + fq) ^ (fr & 7)) << 4);
;         const int roff = rr * 128 + ((p ^ rr) << 4);
;         const int cb = 256 * u.pn + 32 * wc + 4 * p;
; #pragma unroll
;         for (int ai = 0; ai < 2; ++ai) {
;             v4u xv[4][2][2];
; #pragma unroll
;             for (int m = 0; m < 4; ++m) {
;                 const size_t ro = (size_t)(128 * ai + 64 * wr + 16 * m + rr) * DM + (cb & ~7);
; #pragma unroll
;                 for (int bj = 0; bj < 2; ++bj) { xv[m][bj][0] = NTLD((const v4u*)(xb + ro + 128 * bj)); xv[m][bj][1] = NTLD((const v4u*)(xb + ro + 8 * DM + 128 * bj)); }
;             }
; #pragma unroll
;             for (int m = 0; m < 4; ++m) {
;                 const size_t ro = (size_t)(128 * ai + 64 * wr + 16 * m + rr) * DM + cb;
; #pragma unroll
;                 for (int bj = 0; bj < 2; ++bj) {
;                     *(LAS f32x4*)(T + woff0) = acc[ai][bj][m][0]; *(LAS f32x4*)(T + woff1) = acc[ai][bj][m][1];
;                     const f32x4 a0 = *(const LAS f32x4*)(T + roff), a1 = *(const LAS f32x4*)(T + roff + 1024);
;                     const v4u t0 = xv[m][bj][0], t1 = xv[m][bj][1];
;                     const unsigned u0 = (p & 1) ? t0.z : t0.x, u1 = (p & 1) ? t0.w : t0.y, u2 = (p & 1) ? t1.z : t1.x, u3 = (p & 1) ? t1.w : t1.y;
;                     *(f32x4*)(ob + ro + 128 * bj) = (f32x4){bflo(u0), bfhi(u0), bflo(u1), bfhi(u1)} + a0; *(f32x4*)(ob + ro + 8 * DM + 128 * bj) = (f32x4){bflo(u2), bfhi(u2), bflo(u3), bfhi(u3)} + a1;
.LBB0_1239:
	s_add_i32 s6, s4, 0xffffff00
	s_ashr_i32 s5, s4, 31
	s_lshl_b64 s[22:23], s[6:7], 20
	s_add_u32 s6, s49, s22
	s_addc_u32 s15, s50, s23
	s_lshl_b64 s[22:23], s[4:5], 20
	s_add_u32 s17, s56, s22
	s_addc_u32 s22, s57, s23
	s_cmpk_gt_i32 s4, 0xff
	s_cselect_b32 s15, s15, s22
	s_cselect_b32 s6, s6, s17
	s_lshl_b64 s[4:5], s[4:5], 19
	v_mov_b32_e32 v134, v172
	v_mov_b32_e32 v135, v173
	s_add_u32 s4, s41, s4
	s_addc_u32 s5, s42, s5
	v_lshl_add_u32 v128, v135, 4, v134
	s_lshl_b32 s17, s58, 8
	v_ashrrev_i32_e32 v136, 3, v128
	v_and_b32_e32 v128, 7, v134
	s_or_b32 s17, s17, s44
	v_lshlrev_b32_e32 v137, 2, v128
	v_mov_b32_e32 v128, s17
	v_add_u32_e32 v166, s43, v136
	v_bitop3_b32 v128, v137, s54, v128 bitop3:0xc8
	v_ashrrev_i32_e32 v129, 31, v128
	v_ashrrev_i32_e32 v167, 31, v166
	v_lshl_add_u64 v[168:169], v[128:129], 1, s[4:5]
	v_lshlrev_b64 v[128:129], 11, v[166:167]
	v_lshl_add_u64 v[128:129], v[168:169], 0, v[128:129]
	v_mbcnt_lo_u32_b32 v244, -1, 0
	v_mbcnt_hi_u32_b32 v244, -1, v244
	v_and_b32_e32 v244, 1, v244
	v_lshlrev_b32_e32 v244, 3, v244
	v_or_b32_e32 v244, 0x40000, v244
	v_mov_b32_e32 v245, 0
	s_mov_b32 s98, 0x4000
	s_mov_b32 s99, 0
	s_mov_b32 s100, 0x8000
	s_mov_b32 s101, 0
	v_lshl_add_u64 v[244:245], v[128:129], 0, v[244:245]
	global_load_dwordx4 v[182:185], v[128:129], off nt
	global_load_dwordx4 v[190:193], v[128:129], off offset:256 nt
	v_add_co_u32_e32 v130, vcc, s40, v128
	v_or_b32_e32 v128, s17, v137
	s_nop 0
	v_addc_co_u32_e32 v131, vcc, 0, v129, vcc
	global_load_dwordx4 v[186:189], v[130:131], off nt
	global_load_dwordx4 v[194:197], v[130:131], off offset:256 nt
	v_add_u32_e32 v222, 16, v166
	v_mov_b32_e32 v132, s6
	v_mov_b32_e32 v133, s15
	v_ashrrev_i32_e32 v129, 31, v128
	v_ashrrev_i32_e32 v223, 31, v222
	v_bitop3_b32 v138, v134, v135, 7 bitop3:0x6c
	v_add_u32_e32 v135, 4, v135
	v_lshl_add_u64 v[164:165], v[128:129], 2, v[132:133]
	v_lshlrev_b64 v[128:129], 11, v[222:223]
	v_bitop3_b32 v135, v135, v134, 7 bitop3:0x78
	v_lshl_add_u32 v130, v134, 7, s51
	v_lshl_add_u64 v[128:129], v[168:169], 0, v[128:129]
	v_lshl_add_u32 v179, v138, 4, v130
	v_lshl_add_u32 v180, v135, 4, v130
	v_add_co_u32_e32 v130, vcc, s40, v128
	v_add_u32_e32 v224, 32, v166
	s_nop 0
	v_addc_co_u32_e32 v131, vcc, 0, v129, vcc
	global_load_dwordx4 v[198:201], v[128:129], off nt
	global_load_dwordx4 v[202:205], v[128:129], off offset:256 nt
	global_load_dwordx4 v[206:209], v[130:131], off nt
	global_load_dwordx4 v[210:213], v[130:131], off offset:256 nt
	v_ashrrev_i32_e32 v225, 31, v224
	v_lshlrev_b64 v[128:129], 11, v[224:225]
	v_lshl_add_u64 v[128:129], v[168:169], 0, v[128:129]
	v_add_co_u32_e32 v130, vcc, s40, v128
	v_add_u32_e32 v170, 48, v166
	s_nop 0
	v_addc_co_u32_e32 v131, vcc, 0, v129, vcc
	global_load_dwordx4 v[214:217], v[128:129], off nt
	global_load_dwordx4 v[144:147], v[128:129], off offset:256 nt
	global_load_dwordx4 v[218:221], v[130:131], off nt
	global_load_dwordx4 v[148:151], v[130:131], off offset:256 nt
	v_ashrrev_i32_e32 v171, 31, v170
	v_lshlrev_b64 v[128:129], 11, v[170:171]
	v_lshl_add_u64 v[128:129], v[168:169], 0, v[128:129]
	v_lshlrev_b32_e32 v139, 7, v136
	v_bitop3_b32 v136, v136, v134, 7 bitop3:0x78
	v_add_co_u32_e32 v132, vcc, s40, v128
	v_lshlrev_b32_e32 v136, 4, v136
	s_nop 0
	v_addc_co_u32_e32 v133, vcc, 0, v129, vcc
	v_add3_u32 v178, s51, v139, v136
	v_and_b32_e32 v181, 1, v134
	global_load_dwordx4 v[136:139], v[128:129], off nt
	s_nop 0
	global_load_dwordx4 v[128:131], v[128:129], off offset:256 nt
	s_nop 0
	global_load_dwordx4 v[140:143], v[132:133], off nt
	s_nop 0
	global_load_dwordx4 v[132:135], v[132:133], off offset:256 nt
	v_lshl_add_u64 v[246:247], v[244:245], 0, s[98:99]
	global_load_dwordx2 v[228:229], v[244:245], off nt
	global_load_dwordx2 v[230:231], v[246:247], off nt
	global_load_dwordx2 v[232:233], v[244:245], off offset:256 nt
	global_load_dwordx2 v[234:235], v[246:247], off offset:256 nt
	v_lshl_add_u64 v[244:245], v[244:245], 0, s[100:101]
	v_lshl_add_u64 v[246:247], v[244:245], 0, s[98:99]
	global_load_dwordx2 v[236:237], v[244:245], off nt
	global_load_dwordx2 v[238:239], v[244:245], off offset:256 nt
	global_load_dwordx2 v[240:241], v[246:247], off nt
	global_load_dwordx2 v[242:243], v[246:247], off offset:256 nt
	ds_write_b128 v179, v[124:127]
	ds_write_b128 v180, v[120:123]
	ds_read_b128 v[120:123], v178
	ds_read_b128 v[124:127], v178 offset:1024
	v_cmp_eq_u32_e32 vcc, 0, v181
	v_lshlrev_b64 v[226:227], 12, v[166:167]
	v_lshl_add_u64 v[226:227], v[164:165], 0, v[226:227]
	s_waitcnt vmcnt(0)
	v_cndmask_b32_e32 v167, v184, v182, vcc
	v_cndmask_b32_e32 v181, v185, v183, vcc
	v_lshlrev_b32_e32 v182, 16, v167
	v_and_b32_e32 v183, 0xffff0000, v167
	v_lshlrev_b32_e32 v184, 16, v181
	v_and_b32_e32 v185, 0xffff0000, v181
	s_waitcnt lgkmcnt(1)
	v_pk_add_f32 v[120:121], v[120:121], v[182:183]
	v_cndmask_b32_e32 v186, v188, v186, vcc
	v_pk_add_f32 v[122:123], v[122:123], v[184:185]
	v_cndmask_b32_e32 v187, v189, v187, vcc
	global_store_dwordx4 v[226:227], v[120:123], off
	s_nop 1
	v_lshlrev_b32_e32 v120, 16, v186
	v_and_b32_e32 v121, 0xffff0000, v186
	v_lshlrev_b32_e32 v122, 16, v187
	v_and_b32_e32 v123, 0xffff0000, v187
	s_waitcnt lgkmcnt(0)
	v_pk_add_f32 v[120:121], v[124:125], v[120:121]
	v_add_co_u32_e64 v124, s[4:5], s47, v226
	v_pk_add_f32 v[122:123], v[126:127], v[122:123]
	s_nop 0
	v_addc_co_u32_e64 v125, s[4:5], 0, v227, s[4:5]
	global_store_dwordx4 v[124:125], v[120:123], off
	ds_write_b128 v179, v[116:119]
	ds_write_b128 v180, v[112:115]
	ds_read_b128 v[112:115], v178
	ds_read_b128 v[116:119], v178 offset:1024
	v_cndmask_b32_e32 v121, v192, v190, vcc
	v_cndmask_b32_e32 v123, v193, v191, vcc
	v_lshlrev_b32_e32 v120, 16, v121
	v_and_b32_e32 v121, 0xffff0000, v121
	v_lshlrev_b32_e32 v122, 16, v123
	v_and_b32_e32 v123, 0xffff0000, v123
	v_cndmask_b32_e32 v126, v196, v194, vcc
	v_cndmask_b32_e32 v127, v197, v195, vcc
	s_waitcnt lgkmcnt(1)
; #define LAS __attribute__((address_space(3)))
;     __device__ __forceinline__ void operator()(const f32x4 (&acc)[2][2][4][2], const pg8::Unit& u, int wr, int wc, int fr, int fq) const {
;     ...
;             for (int m = 0; m < 4; ++m) {
;                 const size_t ro = (size_t)(128 * ai + 64 * wr + 16 * m + rr) * DM + cb;
; #pragma unroll
;                 for (int bj = 0; bj < 2; ++bj) {
;                     *(LAS f32x4*)(T + woff0) = acc[ai][bj][m][0]; *(LAS f32x4*)(T + woff1) = acc[ai][bj][m][1];
;                     const f32x4 a0 = *(const LAS f32x4*)(T + roff), a1 = *(const LAS f32x4*)(T + roff + 1024);
;                     const v4u t0 = xv[m][bj][0], t1 = xv[m][bj][1];
;                     const unsigned u0 = (p & 1) ? t0.z : t0.x, u1 = (p & 1) ? t0.w : t0.y, u2 = (p & 1) ? t1.z : t1.x, u3 = (p & 1) ? t1.w : t1.y;
;                     *(f32x4*)(ob + ro + 128 * bj) = (f32x4){bflo(u0), bfhi(u0), bflo(u1), bfhi(u1)} + a0; *(f32x4*)(ob + ro + 8 * DM + 128 * bj) = (f32x4){bflo(u2), bfhi(u2), bflo(u3), bfhi(u3)} + a1;
	v_pk_add_f32 v[112:113], v[112:113], v[120:121]
	v_pk_add_f32 v[114:115], v[114:115], v[122:123]
	global_store_dwordx4 v[226:227], v[112:115], off offset:512
	s_nop 1
	v_lshlrev_b32_e32 v112, 16, v126
	v_and_b32_e32 v113, 0xffff0000, v126
	v_lshlrev_b32_e32 v114, 16, v127
	v_and_b32_e32 v115, 0xffff0000, v127
	s_waitcnt lgkmcnt(0)
	v_pk_add_f32 v[112:113], v[116:117], v[112:113]
	v_pk_add_f32 v[114:115], v[118:119], v[114:115]
	global_store_dwordx4 v[124:125], v[112:115], off offset:512
	ds_write_b128 v179, v[108:111]
	ds_write_b128 v180, v[104:107]
	ds_read_b128 v[104:107], v178
	ds_read_b128 v[108:111], v178 offset:1024
	v_cndmask_b32_e32 v115, v200, v198, vcc
	v_cndmask_b32_e32 v117, v201, v199, vcc
	v_lshlrev_b64 v[112:113], 12, v[222:223]
	v_lshlrev_b32_e32 v114, 16, v115
	v_and_b32_e32 v115, 0xffff0000, v115
	v_lshlrev_b32_e32 v116, 16, v117
	v_and_b32_e32 v117, 0xffff0000, v117
	v_lshl_add_u64 v[112:113], v[164:165], 0, v[112:113]
	v_cndmask_b32_e32 v118, v208, v206, vcc
	s_waitcnt lgkmcnt(1)
	v_pk_add_f32 v[104:105], v[104:105], v[114:115]
	v_pk_add_f32 v[106:107], v[106:107], v[116:117]
	v_cndmask_b32_e32 v119, v209, v207, vcc
	global_store_dwordx4 v[112:113], v[104:107], off
	s_nop 1
	v_lshlrev_b32_e32 v104, 16, v118
	v_and_b32_e32 v105, 0xffff0000, v118
	v_lshlrev_b32_e32 v106, 16, v119
	v_and_b32_e32 v107, 0xffff0000, v119
	s_waitcnt lgkmcnt(0)
	v_pk_add_f32 v[104:105], v[108:109], v[104:105]
	v_add_co_u32_e64 v108, s[4:5], s47, v112
	v_pk_add_f32 v[106:107], v[110:111], v[106:107]
	s_nop 0
	v_addc_co_u32_e64 v109, s[4:5], 0, v113, s[4:5]
	global_store_dwordx4 v[108:109], v[104:107], off
	ds_write_b128 v179, v[100:103]
	ds_write_b128 v180, v[96:99]
	ds_read_b128 v[96:99], v178
	ds_read_b128 v[100:103], v178 offset:1024
	v_cndmask_b32_e32 v105, v204, v202, vcc
	v_cndmask_b32_e32 v107, v205, v203, vcc
	v_lshlrev_b32_e32 v104, 16, v105
	v_and_b32_e32 v105, 0xffff0000, v105
	v_lshlrev_b32_e32 v106, 16, v107
	v_and_b32_e32 v107, 0xffff0000, v107
	v_cndmask_b32_e32 v110, v212, v210, vcc
	v_cndmask_b32_e32 v111, v213, v211, vcc
	s_waitcnt lgkmcnt(1)
	v_pk_add_f32 v[96:97], v[96:97], v[104:105]
	v_pk_add_f32 v[98:99], v[98:99], v[106:107]
	global_store_dwordx4 v[112:113], v[96:99], off offset:512
	s_nop 1
	v_lshlrev_b32_e32 v96, 16, v110
	v_and_b32_e32 v97, 0xffff0000, v110
	v_lshlrev_b32_e32 v98, 16, v111
	v_and_b32_e32 v99, 0xffff0000, v111
	s_waitcnt lgkmcnt(0)
	v_pk_add_f32 v[96:97], v[100:101], v[96:97]
	v_pk_add_f32 v[98:99], v[102:103], v[98:99]
	global_store_dwordx4 v[108:109], v[96:99], off offset:512
	ds_write_b128 v179, v[92:95]
	ds_write_b128 v180, v[88:91]
	ds_read_b128 v[88:91], v178
	ds_read_b128 v[92:95], v178 offset:1024
	v_cndmask_b32_e32 v99, v216, v214, vcc
	v_cndmask_b32_e32 v101, v217, v215, vcc
	v_lshlrev_b64 v[96:97], 12, v[224:225]
	v_lshlrev_b32_e32 v98, 16, v99
	v_and_b32_e32 v99, 0xffff0000, v99
	v_lshlrev_b32_e32 v100, 16, v101
	v_and_b32_e32 v101, 0xffff0000, v101
	v_lshl_add_u64 v[96:97], v[164:165], 0, v[96:97]
	v_cndmask_b32_e32 v102, v220, v218, vcc
	s_waitcnt lgkmcnt(1)
	v_pk_add_f32 v[88:89], v[88:89], v[98:99]
	v_pk_add_f32 v[90:91], v[90:91], v[100:101]
	v_cndmask_b32_e32 v103, v221, v219, vcc
	global_store_dwordx4 v[96:97], v[88:91], off
	s_nop 1
	v_lshlrev_b32_e32 v88, 16, v102
	v_and_b32_e32 v89, 0xffff0000, v102
	v_lshlrev_b32_e32 v90, 16, v103
	v_and_b32_e32 v91, 0xffff0000, v103
	s_waitcnt lgkmcnt(0)
	v_pk_add_f32 v[88:89], v[92:93], v[88:89]
	v_add_co_u32_e64 v92, s[4:5], s47, v96
	v_pk_add_f32 v[90:91], v[94:95], v[90:91]
	s_nop 0
	v_addc_co_u32_e64 v93, s[4:5], 0, v97, s[4:5]
	global_store_dwordx4 v[92:93], v[88:91], off
	ds_write_b128 v179, v[84:87]
	ds_write_b128 v180, v[80:83]
	ds_read_b128 v[80:83], v178
	ds_read_b128 v[84:87], v178 offset:1024
	v_cndmask_b32_e32 v89, v146, v144, vcc
	v_cndmask_b32_e32 v91, v147, v145, vcc
	v_lshlrev_b32_e32 v88, 16, v89
	v_and_b32_e32 v89, 0xffff0000, v89
	v_lshlrev_b32_e32 v90, 16, v91
	v_and_b32_e32 v91, 0xffff0000, v91
	v_cndmask_b32_e32 v94, v150, v148, vcc
	v_cndmask_b32_e32 v95, v151, v149, vcc
	s_waitcnt lgkmcnt(1)
	v_pk_add_f32 v[80:81], v[80:81], v[88:89]
	v_pk_add_f32 v[82:83], v[82:83], v[90:91]
	global_store_dwordx4 v[96:97], v[80:83], off offset:512
	s_nop 1
	v_lshlrev_b32_e32 v80, 16, v94
	v_and_b32_e32 v81, 0xffff0000, v94
	v_lshlrev_b32_e32 v82, 16, v95
	v_and_b32_e32 v83, 0xffff0000, v95
	s_waitcnt lgkmcnt(0)
	v_pk_add_f32 v[80:81], v[84:85], v[80:81]
	v_pk_add_f32 v[82:83], v[86:87], v[82:83]
	global_store_dwordx4 v[92:93], v[80:83], off offset:512
	ds_write_b128 v179, v[76:79]
	ds_write_b128 v180, v[72:75]
	ds_read_b128 v[72:75], v178
	ds_read_b128 v[76:79], v178 offset:1024
	v_cndmask_b32_e32 v83, v138, v136, vcc
	v_cndmask_b32_e32 v85, v139, v137, vcc
	v_lshlrev_b64 v[80:81], 12, v[170:171]
	v_lshlrev_b32_e32 v82, 16, v83
	v_and_b32_e32 v83, 0xffff0000, v83
	v_lshlrev_b32_e32 v84, 16, v85
	v_and_b32_e32 v85, 0xffff0000, v85
	v_lshl_add_u64 v[80:81], v[164:165], 0, v[80:81]
	v_cndmask_b32_e32 v86, v142, v140, vcc
	s_waitcnt lgkmcnt(1)
	v_pk_add_f32 v[72:73], v[72:73], v[82:83]
	v_pk_add_f32 v[74:75], v[74:75], v[84:85]
	v_cndmask_b32_e32 v87, v143, v141, vcc
	global_store_dwordx4 v[80:81], v[72:75], off
	s_nop 1
	v_lshlrev_b32_e32 v72, 16, v86
	v_and_b32_e32 v73, 0xffff0000, v86
	v_lshlrev_b32_e32 v74, 16, v87
	v_and_b32_e32 v75, 0xffff0000, v87
	s_waitcnt lgkmcnt(0)
; #define LAS __attribute__((address_space(3)))
; #define NTLD(p) __builtin_nontemporal_load(p)
;     __device__ __forceinline__ void operator()(const f32x4 (&acc)[2][2][4][2], const pg8::Unit& u, int wr, int wc, int fr, int fq) const {
;     ...
;         for (int ai = 0; ai < 2; ++ai) {
;             v4u xv[4][2][2];
; #pragma unroll
;             for (int m = 0; m < 4; ++m) {
;                 const size_t ro = (size_t)(128 * ai + 64 * wr + 16 * m + rr) * DM + (cb & ~7);
; #pragma unroll
;                 for (int bj = 0; bj < 2; ++bj) { xv[m][bj][0] = NTLD((const v4u*)(xb + ro + 128 * bj)); xv[m][bj][1] = NTLD((const v4u*)(xb + ro + 8 * DM + 128 * bj)); }
;             }
; #pragma unroll
;             for (int m = 0; m < 4; ++m) {
;                 const size_t ro = (size_t)(128 * ai + 64 * wr + 16 * m + rr) * DM + cb;
; #pragma unroll
;                 for (int bj = 0; bj < 2; ++bj) {
;                     *(LAS f32x4*)(T + woff0) = acc[ai][bj][m][0]; *(LAS f32x4*)(T + woff1) = acc[ai][bj][m][1];
;                     const f32x4 a0 = *(const LAS f32x4*)(T + roff), a1 = *(const LAS f32x4*)(T + roff + 1024);
;                     const v4u t0 = xv[m][bj][0], t1 = xv[m][bj][1];
;                     const unsigned u0 = (p & 1) ? t0.z : t0.x, u1 = (p & 1) ? t0.w : t0.y, u2 = (p & 1) ? t1.z : t1.x, u3 = (p & 1) ? t1.w : t1.y;
;                     *(f32x4*)(ob + ro + 128 * bj) = (f32x4){bflo(u0), bfhi(u0), bflo(u1), bfhi(u1)} + a0; *(f32x4*)(ob + ro + 8 * DM + 128 * bj) = (f32x4){bflo(u2), bfhi(u2), bflo(u3), bfhi(u3)} + a1;
	v_pk_add_f32 v[72:73], v[76:77], v[72:73]
	v_add_co_u32_e64 v76, s[4:5], s47, v80
	v_pk_add_f32 v[74:75], v[78:79], v[74:75]
	s_nop 0
	v_addc_co_u32_e64 v77, s[4:5], 0, v81, s[4:5]
	global_store_dwordx4 v[76:77], v[72:75], off
	ds_write_b128 v179, v[68:71]
	ds_write_b128 v180, v[64:67]
	ds_read_b128 v[64:67], v178
	ds_read_b128 v[68:71], v178 offset:1024
	v_cndmask_b32_e32 v73, v130, v128, vcc
	v_cndmask_b32_e32 v75, v131, v129, vcc
	v_lshlrev_b32_e32 v72, 16, v73
	v_and_b32_e32 v73, 0xffff0000, v73
	v_lshlrev_b32_e32 v74, 16, v75
	v_and_b32_e32 v75, 0xffff0000, v75
	v_cndmask_b32_e32 v78, v134, v132, vcc
	v_cndmask_b32_e32 v79, v135, v133, vcc
	s_waitcnt lgkmcnt(1)
	v_pk_add_f32 v[64:65], v[64:65], v[72:73]
	v_pk_add_f32 v[66:67], v[66:67], v[74:75]
	global_store_dwordx4 v[80:81], v[64:67], off offset:512
	v_add_u32_e32 v130, 0x80, v166
	v_ashrrev_i32_e32 v131, 31, v130
	v_lshlrev_b32_e32 v64, 16, v78
	v_and_b32_e32 v65, 0xffff0000, v78
	v_lshlrev_b32_e32 v66, 16, v79
	v_and_b32_e32 v67, 0xffff0000, v79
	s_waitcnt lgkmcnt(0)
	v_pk_add_f32 v[64:65], v[68:69], v[64:65]
	v_pk_add_f32 v[66:67], v[70:71], v[66:67]
	global_store_dwordx4 v[76:77], v[64:67], off offset:512
	v_add_u32_e32 v132, 0x90, v166
	v_ashrrev_i32_e32 v133, 31, v132
	v_lshlrev_b64 v[64:65], 11, v[130:131]
	v_lshl_add_u64 v[64:65], v[168:169], 0, v[64:65]
	v_add_co_u32_e64 v66, s[4:5], s40, v64
	v_add_u32_e32 v134, 0xa0, v166
	s_nop 0
	v_addc_co_u32_e64 v67, s[4:5], 0, v65, s[4:5]
	v_lshlrev_b64 v[64:65], 11, v[132:133]
	v_lshl_add_u64 v[64:65], v[168:169], 0, v[64:65]
	v_add_co_u32_e64 v66, s[4:5], s40, v64
	v_ashrrev_i32_e32 v135, 31, v134
	s_nop 0
	v_addc_co_u32_e64 v67, s[4:5], 0, v65, s[4:5]
	v_lshlrev_b64 v[64:65], 11, v[134:135]
	v_lshl_add_u64 v[64:65], v[168:169], 0, v[64:65]
	v_add_co_u32_e64 v66, s[4:5], s40, v64
	v_add_u32_e32 v80, 0xb0, v166
	s_nop 0
	v_addc_co_u32_e64 v67, s[4:5], 0, v65, s[4:5]
	global_load_dwordx4 v[114:117], v[64:65], off nt
	global_load_dwordx4 v[118:121], v[64:65], off offset:256 nt
	global_load_dwordx4 v[122:125], v[66:67], off nt
	global_load_dwordx4 v[126:129], v[66:67], off offset:256 nt
	v_ashrrev_i32_e32 v81, 31, v80
	v_lshlrev_b64 v[64:65], 11, v[80:81]
	v_lshl_add_u64 v[64:65], v[168:169], 0, v[64:65]
	v_add_co_u32_e64 v68, s[4:5], s40, v64
	v_lshlrev_b64 v[130:131], 12, v[130:131]
	s_nop 0
	v_addc_co_u32_e64 v69, s[4:5], 0, v65, s[4:5]
	global_load_dwordx4 v[72:75], v[64:65], off nt
	s_nop 0
	global_load_dwordx4 v[64:67], v[64:65], off offset:256 nt
	s_nop 0
	global_load_dwordx4 v[76:79], v[68:69], off nt
	s_nop 0
	global_load_dwordx4 v[68:71], v[68:69], off offset:256 nt
	ds_write_b128 v179, v[60:63]
	ds_write_b128 v180, v[56:59]
	ds_read_b128 v[56:59], v178
	ds_read_b128 v[60:63], v178 offset:1024
	v_lshl_add_u64 v[130:131], v[164:165], 0, v[130:131]
	v_mov_b32_e32 v82, v228
	v_mov_b32_e32 v83, v229
	v_mov_b32_e32 v84, v228
	v_mov_b32_e32 v85, v229
	v_mov_b32_e32 v86, v230
	v_mov_b32_e32 v87, v231
	v_mov_b32_e32 v88, v230
	v_mov_b32_e32 v89, v231
	v_mov_b32_e32 v90, v232
	v_mov_b32_e32 v91, v233
	v_mov_b32_e32 v92, v232
	v_mov_b32_e32 v93, v233
	v_mov_b32_e32 v94, v234
	v_mov_b32_e32 v95, v235
	v_mov_b32_e32 v96, v234
	v_mov_b32_e32 v97, v235
	v_mov_b32_e32 v98, v236
	v_mov_b32_e32 v99, v237
	v_mov_b32_e32 v100, v236
	v_mov_b32_e32 v101, v237
	v_mov_b32_e32 v102, v238
	v_mov_b32_e32 v103, v239
	v_mov_b32_e32 v104, v238
	v_mov_b32_e32 v105, v239
	v_mov_b32_e32 v106, v240
	v_mov_b32_e32 v107, v241
	v_mov_b32_e32 v108, v240
	v_mov_b32_e32 v109, v241
	v_mov_b32_e32 v110, v242
	v_mov_b32_e32 v111, v243
	v_mov_b32_e32 v112, v242
	v_mov_b32_e32 v113, v243
	v_cndmask_b32_e32 v84, v84, v82, vcc
	v_cndmask_b32_e32 v85, v85, v83, vcc
	v_lshlrev_b32_e32 v82, 16, v84
	v_and_b32_e32 v83, 0xffff0000, v84
	v_lshlrev_b32_e32 v84, 16, v85
	v_and_b32_e32 v85, 0xffff0000, v85
	v_cndmask_b32_e32 v86, v88, v86, vcc
	s_waitcnt lgkmcnt(1)
	v_pk_add_f32 v[56:57], v[56:57], v[82:83]
	v_pk_add_f32 v[58:59], v[58:59], v[84:85]
	v_cndmask_b32_e32 v87, v89, v87, vcc
	global_store_dwordx4 v[130:131], v[56:59], off
	s_nop 1
	v_lshlrev_b32_e32 v56, 16, v86
	v_and_b32_e32 v57, 0xffff0000, v86
	v_lshlrev_b32_e32 v58, 16, v87
	v_and_b32_e32 v59, 0xffff0000, v87
	s_waitcnt lgkmcnt(0)
	v_pk_add_f32 v[56:57], v[60:61], v[56:57]
	v_add_co_u32_e64 v60, s[4:5], s47, v130
	v_pk_add_f32 v[58:59], v[62:63], v[58:59]
	s_nop 0
	v_addc_co_u32_e64 v61, s[4:5], 0, v131, s[4:5]
	global_store_dwordx4 v[60:61], v[56:59], off
	ds_write_b128 v179, v[52:55]
	ds_write_b128 v180, v[48:51]
	ds_read_b128 v[48:51], v178
	ds_read_b128 v[52:55], v178 offset:1024
	v_cndmask_b32_e32 v57, v92, v90, vcc
	v_cndmask_b32_e32 v59, v93, v91, vcc
	v_lshlrev_b32_e32 v56, 16, v57
	v_and_b32_e32 v57, 0xffff0000, v57
	v_lshlrev_b32_e32 v58, 16, v59
	v_and_b32_e32 v59, 0xffff0000, v59
	v_cndmask_b32_e32 v62, v96, v94, vcc
	v_cndmask_b32_e32 v63, v97, v95, vcc
	s_waitcnt lgkmcnt(1)
	v_pk_add_f32 v[48:49], v[48:49], v[56:57]
	v_pk_add_f32 v[50:51], v[50:51], v[58:59]
	global_store_dwordx4 v[130:131], v[48:51], off offset:512
	s_nop 1
	v_lshlrev_b32_e32 v48, 16, v62
	v_and_b32_e32 v49, 0xffff0000, v62
	v_lshlrev_b32_e32 v50, 16, v63
	v_and_b32_e32 v51, 0xffff0000, v63
	s_waitcnt lgkmcnt(0)
	v_pk_add_f32 v[48:49], v[52:53], v[48:49]
	v_pk_add_f32 v[50:51], v[54:55], v[50:51]
	global_store_dwordx4 v[60:61], v[48:51], off offset:512
	ds_write_b128 v179, v[44:47]
	ds_write_b128 v180, v[40:43]
	ds_read_b128 v[40:43], v178
	ds_read_b128 v[44:47], v178 offset:1024
	v_cndmask_b32_e32 v51, v100, v98, vcc
	v_cndmask_b32_e32 v53, v101, v99, vcc
	v_lshlrev_b64 v[48:49], 12, v[132:133]
	v_lshlrev_b32_e32 v50, 16, v51
	v_and_b32_e32 v51, 0xffff0000, v51
	v_lshlrev_b32_e32 v52, 16, v53
	v_and_b32_e32 v53, 0xffff0000, v53
	v_lshl_add_u64 v[48:49], v[164:165], 0, v[48:49]
	v_cndmask_b32_e32 v54, v108, v106, vcc
	s_waitcnt lgkmcnt(1)
; #define PG8_BAR __builtin_amdgcn_s_barrier()
; #define LAS __attribute__((address_space(3)))
; template <class Epi, class Sched, bool ALIGN_EPI = false, bool SP2 = false>
; __device__ __forceinline__ void gemm_phase(PG8_LAS unsigned char* lds, const Gemm g, const Sched& S, const Epi& E) {
;     ...
;         if constexpr (ALIGN_EPI) { if (wr == 0) PG8_BAR; }
;         if constexpr (!Epi::AFTER_DRAIN) { E(acc, cur, wr, wc, fr, fq); S.done(cur); }
;         if (!has_next) break;
; #pragma unroll
;         for (int a = 0; a < 2; ++a)
; #pragma unroll
;             for (int b = 0; b < 2; ++b)
; #pragma unroll
;                 for (int m = 0; m < 4; ++m)
; #pragma unroll
;                     for (int n = 0; n < 2; ++n) acc[a][b][m][n] = (f32x4){0.f, 0.f, 0.f, 0.f};
;         cur = nxt; cA = nA; cB = nB; ++ui;
;         if constexpr (ALIGN_EPI) { if (wr == 1) PG8_BAR; }
;     }
;     __device__ __forceinline__ void operator()(const f32x4 (&acc)[2][2][4][2], const pg8::Unit& u, int wr, int wc, int fr, int fq) const {
;     ...
;             for (int m = 0; m < 4; ++m) {
;                 const size_t ro = (size_t)(128 * ai + 64 * wr + 16 * m + rr) * DM + cb;
; #pragma unroll
;                 for (int bj = 0; bj < 2; ++bj) {
;                     *(LAS f32x4*)(T + woff0) = acc[ai][bj][m][0]; *(LAS f32x4*)(T + woff1) = acc[ai][bj][m][1];
;                     const f32x4 a0 = *(const LAS f32x4*)(T + roff), a1 = *(const LAS f32x4*)(T + roff + 1024);
;                     const v4u t0 = xv[m][bj][0], t1 = xv[m][bj][1];
;                     const unsigned u0 = (p & 1) ? t0.z : t0.x, u1 = (p & 1) ? t0.w : t0.y, u2 = (p & 1) ? t1.z : t1.x, u3 = (p & 1) ? t1.w : t1.y;
;                     *(f32x4*)(ob + ro + 128 * bj) = (f32x4){bflo(u0), bfhi(u0), bflo(u1), bfhi(u1)} + a0; *(f32x4*)(ob + ro + 8 * DM + 128 * bj) = (f32x4){bflo(u2), bfhi(u2), bflo(u3), bfhi(u3)} + a1;
	v_pk_add_f32 v[40:41], v[40:41], v[50:51]
	v_pk_add_f32 v[42:43], v[42:43], v[52:53]
	v_cndmask_b32_e32 v55, v109, v107, vcc
	global_store_dwordx4 v[48:49], v[40:43], off
	s_nop 1
	v_lshlrev_b32_e32 v40, 16, v54
	v_and_b32_e32 v41, 0xffff0000, v54
	v_lshlrev_b32_e32 v42, 16, v55
	v_and_b32_e32 v43, 0xffff0000, v55
	s_waitcnt lgkmcnt(0)
	v_pk_add_f32 v[40:41], v[44:45], v[40:41]
	v_add_co_u32_e64 v44, s[4:5], s47, v48
	v_pk_add_f32 v[42:43], v[46:47], v[42:43]
	s_nop 0
	v_addc_co_u32_e64 v45, s[4:5], 0, v49, s[4:5]
	global_store_dwordx4 v[44:45], v[40:43], off
	ds_write_b128 v179, v[36:39]
	ds_write_b128 v180, v[32:35]
	ds_read_b128 v[32:35], v178
	ds_read_b128 v[36:39], v178 offset:1024
	v_cndmask_b32_e32 v41, v104, v102, vcc
	v_cndmask_b32_e32 v43, v105, v103, vcc
	v_lshlrev_b32_e32 v40, 16, v41
	v_and_b32_e32 v41, 0xffff0000, v41
	v_lshlrev_b32_e32 v42, 16, v43
	v_and_b32_e32 v43, 0xffff0000, v43
	v_cndmask_b32_e32 v46, v112, v110, vcc
	v_cndmask_b32_e32 v47, v113, v111, vcc
	s_waitcnt lgkmcnt(1)
	v_pk_add_f32 v[32:33], v[32:33], v[40:41]
	v_pk_add_f32 v[34:35], v[34:35], v[42:43]
	global_store_dwordx4 v[48:49], v[32:35], off offset:512
	s_nop 1
	v_lshlrev_b32_e32 v32, 16, v46
	v_and_b32_e32 v33, 0xffff0000, v46
	v_lshlrev_b32_e32 v34, 16, v47
	v_and_b32_e32 v35, 0xffff0000, v47
	s_waitcnt lgkmcnt(0)
	v_pk_add_f32 v[32:33], v[36:37], v[32:33]
	v_pk_add_f32 v[34:35], v[38:39], v[34:35]
	global_store_dwordx4 v[44:45], v[32:35], off offset:512
	ds_write_b128 v179, v[28:31]
	ds_write_b128 v180, v[24:27]
	ds_read_b128 v[24:27], v178
	ds_read_b128 v[28:31], v178 offset:1024
	s_waitcnt vmcnt(15)
	v_cndmask_b32_e32 v35, v116, v114, vcc
	v_cndmask_b32_e32 v37, v117, v115, vcc
	v_lshlrev_b64 v[32:33], 12, v[134:135]
	v_lshlrev_b32_e32 v34, 16, v35
	v_and_b32_e32 v35, 0xffff0000, v35
	v_lshlrev_b32_e32 v36, 16, v37
	v_and_b32_e32 v37, 0xffff0000, v37
	v_lshl_add_u64 v[32:33], v[164:165], 0, v[32:33]
	s_waitcnt vmcnt(13)
	v_cndmask_b32_e32 v38, v124, v122, vcc
	s_waitcnt lgkmcnt(1)
	v_pk_add_f32 v[24:25], v[24:25], v[34:35]
	v_pk_add_f32 v[26:27], v[26:27], v[36:37]
	v_cndmask_b32_e32 v39, v125, v123, vcc
	global_store_dwordx4 v[32:33], v[24:27], off
	s_nop 1
	v_lshlrev_b32_e32 v24, 16, v38
	v_and_b32_e32 v25, 0xffff0000, v38
	v_lshlrev_b32_e32 v26, 16, v39
	v_and_b32_e32 v27, 0xffff0000, v39
	s_waitcnt lgkmcnt(0)
	v_pk_add_f32 v[24:25], v[28:29], v[24:25]
	v_add_co_u32_e64 v28, s[4:5], s47, v32
	v_pk_add_f32 v[26:27], v[30:31], v[26:27]
	s_nop 0
	v_addc_co_u32_e64 v29, s[4:5], 0, v33, s[4:5]
	global_store_dwordx4 v[28:29], v[24:27], off
	ds_write_b128 v179, v[20:23]
	ds_write_b128 v180, v[16:19]
	ds_read_b128 v[16:19], v178
	ds_read_b128 v[20:23], v178 offset:1024
	v_cndmask_b32_e32 v25, v120, v118, vcc
	v_cndmask_b32_e32 v27, v121, v119, vcc
	v_lshlrev_b32_e32 v24, 16, v25
	v_and_b32_e32 v25, 0xffff0000, v25
	v_lshlrev_b32_e32 v26, 16, v27
	v_and_b32_e32 v27, 0xffff0000, v27
	s_waitcnt vmcnt(14)
	v_cndmask_b32_e32 v30, v128, v126, vcc
	v_cndmask_b32_e32 v31, v129, v127, vcc
	s_waitcnt lgkmcnt(1)
	v_pk_add_f32 v[16:17], v[16:17], v[24:25]
	v_pk_add_f32 v[18:19], v[18:19], v[26:27]
	global_store_dwordx4 v[32:33], v[16:19], off offset:512
	s_nop 1
	v_lshlrev_b32_e32 v16, 16, v30
	v_and_b32_e32 v17, 0xffff0000, v30
	v_lshlrev_b32_e32 v18, 16, v31
	v_and_b32_e32 v19, 0xffff0000, v31
	s_waitcnt lgkmcnt(0)
	v_pk_add_f32 v[16:17], v[20:21], v[16:17]
	v_pk_add_f32 v[18:19], v[22:23], v[18:19]
	global_store_dwordx4 v[28:29], v[16:19], off offset:512
	ds_write_b128 v179, v[12:15]
	ds_write_b128 v180, v[8:11]
	ds_read_b128 v[8:11], v178
	ds_read_b128 v[12:15], v178 offset:1024
	s_waitcnt vmcnt(15)
	v_cndmask_b32_e32 v19, v74, v72, vcc
	v_cndmask_b32_e32 v21, v75, v73, vcc
	v_lshlrev_b64 v[16:17], 12, v[80:81]
	v_lshlrev_b32_e32 v18, 16, v19
	v_and_b32_e32 v19, 0xffff0000, v19
	v_lshlrev_b32_e32 v20, 16, v21
	v_and_b32_e32 v21, 0xffff0000, v21
	v_lshl_add_u64 v[16:17], v[164:165], 0, v[16:17]
	s_waitcnt vmcnt(13)
	v_cndmask_b32_e32 v22, v78, v76, vcc
	s_waitcnt lgkmcnt(1)
	v_pk_add_f32 v[8:9], v[8:9], v[18:19]
	v_pk_add_f32 v[10:11], v[10:11], v[20:21]
	v_cndmask_b32_e32 v23, v79, v77, vcc
	global_store_dwordx4 v[16:17], v[8:11], off
	s_nop 1
	v_lshlrev_b32_e32 v8, 16, v22
	v_and_b32_e32 v9, 0xffff0000, v22
	v_lshlrev_b32_e32 v10, 16, v23
	v_and_b32_e32 v11, 0xffff0000, v23
	s_waitcnt lgkmcnt(0)
	v_pk_add_f32 v[8:9], v[12:13], v[8:9]
	v_add_co_u32_e64 v12, s[4:5], s47, v16
	v_pk_add_f32 v[10:11], v[14:15], v[10:11]
	s_nop 0
	v_addc_co_u32_e64 v13, s[4:5], 0, v17, s[4:5]
	global_store_dwordx4 v[12:13], v[8:11], off
	ds_write_b128 v179, v[4:7]
	ds_write_b128 v180, v[0:3]
	ds_read_b128 v[0:3], v178
	ds_read_b128 v[4:7], v178 offset:1024
	v_cndmask_b32_e32 v9, v66, v64, vcc
	v_cndmask_b32_e32 v11, v67, v65, vcc
	v_lshlrev_b32_e32 v8, 16, v9
	v_and_b32_e32 v9, 0xffff0000, v9
	v_lshlrev_b32_e32 v10, 16, v11
	v_and_b32_e32 v11, 0xffff0000, v11
	s_waitcnt vmcnt(14)
	v_cndmask_b32_e32 v14, v70, v68, vcc
	v_cndmask_b32_e32 v15, v71, v69, vcc
	s_waitcnt lgkmcnt(1)
	v_pk_add_f32 v[0:1], v[0:1], v[8:9]
	v_pk_add_f32 v[2:3], v[2:3], v[10:11]
	global_store_dwordx4 v[16:17], v[0:3], off offset:512
	s_andn2_b64 vcc, exec, s[0:1]
	s_mov_b64 s[0:1], -1
	v_lshlrev_b32_e32 v0, 16, v14
	v_and_b32_e32 v1, 0xffff0000, v14
	v_lshlrev_b32_e32 v2, 16, v15
	v_and_b32_e32 v3, 0xffff0000, v15
	s_waitcnt lgkmcnt(0)
	v_pk_add_f32 v[0:1], v[4:5], v[0:1]
	v_pk_add_f32 v[2:3], v[6:7], v[2:3]
	global_store_dwordx4 v[12:13], v[0:3], off offset:512
	s_cbranch_vccnz .LBB0_1228
	s_andn2_b64 vcc, exec, s[8:9]
	s_cbranch_vccnz .LBB0_1227
	s_barrier
	s_branch .LBB0_1227

; __global__ void __launch_bounds__(NWAVES * 64, 2) hymba_fwd(Args args) {
;     extern __shared__ __attribute__((aligned(16))) unsigned char lds[];
	.amdhsa_kernel _Z9hymba_fwd4Args
		.amdhsa_group_segment_fixed_size 0
		.amdhsa_private_segment_fixed_size 0
		.amdhsa_kernarg_size 392
		.amdhsa_user_sgpr_count 2
		.amdhsa_user_sgpr_dispatch_ptr 0
		.amdhsa_user_sgpr_queue_ptr 0
		.amdhsa_user_sgpr_kernarg_segment_ptr 1
		.amdhsa_user_sgpr_dispatch_id 0
		.amdhsa_user_sgpr_kernarg_preload_length 0
		.amdhsa_user_sgpr_kernarg_preload_offset 0
		.amdhsa_user_sgpr_private_segment_size 0
		.amdhsa_uses_dynamic_stack 0
		.amdhsa_enable_private_segment 0
		.amdhsa_system_sgpr_workgroup_id_x 1
		.amdhsa_system_sgpr_workgroup_id_y 0
		.amdhsa_system_sgpr_workgroup_id_z 0
		.amdhsa_system_sgpr_workgroup_info 0
		.amdhsa_system_vgpr_workitem_id 0
		.amdhsa_next_free_vgpr 248
		.amdhsa_next_free_sgpr 102
		.amdhsa_accum_offset 248
		.amdhsa_reserve_vcc 1
		.amdhsa_float_round_mode_32 0
		.amdhsa_float_round_mode_16_64 0
		.amdhsa_float_denorm_mode_32 3
		.amdhsa_float_denorm_mode_16_64 3
		.amdhsa_dx10_clamp 1
		.amdhsa_ieee_mode 1
		.amdhsa_fp16_overflow 0
		.amdhsa_tg_split 0
		.amdhsa_exception_fp_ieee_invalid_op 0
		.amdhsa_exception_fp_denorm_src 0
		.amdhsa_exception_fp_ieee_div_zero 0
		.amdhsa_exception_fp_ieee_overflow 0
		.amdhsa_exception_fp_ieee_underflow 0
		.amdhsa_exception_fp_ieee_inexact 0
		.amdhsa_exception_int_div_zero 0
	.end_amdhsa_kernel

; __global__ void __launch_bounds__(NWAVES * 64, 2) hymba_fwd(Args args) {
;     extern __shared__ __attribute__((aligned(16))) unsigned char lds[];
amdhsa.kernels:
  - .agpr_count:     0
    .args:
      - .offset:         0
        .size:           136
        .value_kind:     by_value
      - .offset:         136
        .size:           4
        .value_kind:     hidden_block_count_x
      - .offset:         140
        .size:           4
        .value_kind:     hidden_block_count_y
      - .offset:         144
        .size:           4
        .value_kind:     hidden_block_count_z
      - .offset:         148
        .size:           2
        .value_kind:     hidden_group_size_x
      - .offset:         150
        .size:           2
        .value_kind:     hidden_group_size_y
      - .offset:         152
        .size:           2
        .value_kind:     hidden_group_size_z
      - .offset:         154
        .size:           2
        .value_kind:     hidden_remainder_x
      - .offset:         156
        .size:           2
        .value_kind:     hidden_remainder_y
      - .offset:         158
        .size:           2
        .value_kind:     hidden_remainder_z
      - .offset:         176
        .size:           8
        .value_kind:     hidden_global_offset_x
      - .offset:         184
        .size:           8
        .value_kind:     hidden_global_offset_y
      - .offset:         192
        .size:           8
        .value_kind:     hidden_global_offset_z
      - .offset:         200
        .size:           2
        .value_kind:     hidden_grid_dims
      - .offset:         256
        .size:           4
        .value_kind:     hidden_dynamic_lds_size
    .group_segment_fixed_size: 0
    .kernarg_segment_align: 8
    .kernarg_segment_size: 392
    .language:       OpenCL C
    .language_version:
      - 2
      - 0
    .max_flat_workgroup_size: 512
    .name:           _Z9hymba_fwd4Args
    .private_segment_fixed_size: 0
    .sgpr_count:     108
    .sgpr_spill_count: 112
    .symbol:         _Z9hymba_fwd4Args.kd
    .uniform_work_group_size: 1
    .uses_dynamic_stack: false
    .vgpr_count:     248
    .vgpr_spill_count: 0
    .wavefront_size: 64
